# same as previous plus grid-size guard: static attention assignment only when the grid has 512 workgroups, otherwise the original atomic queue
# baseline (speedup 1.0000x reference)
.LBB0_229:
	v_readlane_b32 s4, v254, 63
	v_readlane_b32 s5, v255, 0
	s_and_b64 vcc, exec, s[4:5]
	s_cbranch_vccz .LBB0_235
	s_barrier
	s_mov_b64 s[4:5], exec
	v_readlane_b32 s20, v252, 26
	v_readlane_b32 s21, v252, 27
	s_and_b64 s[20:21], s[4:5], s[20:21]
	s_mov_b64 exec, s[20:21]
	s_cbranch_execz .LBB0_234
	s_mov_b64 s[24:25], exec
	v_mbcnt_lo_u32_b32 v0, s24, 0
	v_mbcnt_hi_u32_b32 v0, s25, v0
	v_cmp_eq_u32_e32 vcc, 0, v0
	s_and_saveexec_b64 s[20:21], vcc
	s_cbranch_execz .LBB0_233
	s_cmpk_eq_u32 s81, 0x200
	s_cbranch_scc1 .Lattn_static
	s_bcnt1_i32_b64 s24, s[24:25]
	s_waitcnt lgkmcnt(0)
	v_mov_b32_e32 v2, s24
	v_readlane_b32 s24, v255, 13
	v_readlane_b32 s25, v255, 14
	s_nop 4
	global_atomic_add v2, v1, v2, s[24:25] sc0
	s_branch .LBB0_233
.Lattn_static:
	s_waitcnt lgkmcnt(0)
	ds_read_b32 v2, v196 offset:4
	v_readlane_b32 s99, v255, 12
	s_waitcnt lgkmcnt(0)
	v_readfirstlane_b32 s24, v2
	s_nop 3
	s_and_b32 s25, s99, 7
	s_lshl_b32 s25, s25, 6
	s_lshr_b32 s26, s99, 3
	s_or_b32 s25, s25, s26
	s_add_i32 s25, s25, 0x100
	s_cmpk_lt_u32 s99, 0x100
	s_cselect_b32 s26, 0, 1
	s_add_i32 s26, s26, s24
	s_add_i32 s24, s24, 1
	s_cmp_eq_u32 s26, 1
	s_cselect_b32 s98, s25, 0x300
	s_cmp_eq_u32 s26, 0
	s_cselect_b32 s98, s99, s98
	s_cmp_gt_u32 s26, 1
	s_cselect_b32 s24, 0, s24
	v_mov_b32_e32 v2, s24
	ds_write_b32 v196, v2 offset:4
	v_mov_b32_e32 v2, s98
